# RG-LRU scan: software-pipelined LDS reads (depth 8) instead of one wait per step
# speedup vs baseline: 1.0097x; 1.0097x over previous
.LBB0_270:
	s_waitcnt lgkmcnt(0)
	s_barrier
	ds_read_b128 v[40:43], v117
	ds_read_b128 v[36:39], v117 offset:64
	ds_read_b128 v[44:47], v118 offset:9216
	ds_read_b128 v[48:51], v118 offset:18432
	ds_read_b128 v[52:55], v118 offset:9280
	s_waitcnt lgkmcnt(2)
	v_mfma_f32_16x16x32_bf16 v[44:47], v[40:43], v[44:47], 0
	ds_read_u16 v3, v119
	s_waitcnt lgkmcnt(0)
	v_lshlrev_b32_e32 v3, 16, v3
	v_mfma_f32_16x16x32_bf16 v[44:47], v[36:39], v[52:55], v[44:47]
	ds_read_b128 v[52:55], v118 offset:18496
	v_mfma_f32_16x16x32_bf16 v[48:51], v[40:43], v[48:51], 0
	s_waitcnt lgkmcnt(0)
	v_mfma_f32_16x16x32_bf16 v[48:51], v[36:39], v[52:55], v[48:51]
	s_nop 3
	v_add_f32_e32 v1, v97, v44
	v_mul_f32_e32 v1, 0xbfb8aa3b, v1
	v_exp_f32_e32 v1, v1
	s_nop 0
	v_add_f32_e32 v1, 1.0, v1
	v_rcp_f32_e32 v1, v1
	v_add_f32_e32 v2, v98, v48
	v_mul_f32_e32 v2, 0xbfb8aa3b, v2
	v_exp_f32_e32 v2, v2
	v_mul_f32_e32 v1, v105, v1
	v_mul_f32_e32 v1, 0x3fb8aa3b, v1
	v_exp_f32_e32 v1, v1
	v_add_f32_e32 v2, 1.0, v2
	v_rcp_f32_e32 v2, v2
	v_fma_f32 v44, -v1, v1, 1.0
	v_max_f32_e32 v44, 0, v44
	v_sqrt_f32_e32 v44, v44
	v_mul_f32_e32 v2, v2, v3
	v_mul_f32_e32 v2, v2, v44
	ds_write_b32 v109, v1 offset:27648
	ds_write_b32 v109, v2 offset:44288
	v_add_f32_e32 v1, v97, v45
	v_mul_f32_e32 v1, 0xbfb8aa3b, v1
	v_exp_f32_e32 v1, v1
	v_add_f32_e32 v2, v98, v49
	v_mul_f32_e32 v2, 0xbfb8aa3b, v2
	v_exp_f32_e32 v2, v2
	v_add_f32_e32 v1, 1.0, v1
	v_rcp_f32_e32 v1, v1
	ds_read_u16 v3, v120
	v_add_f32_e32 v2, 1.0, v2
	v_rcp_f32_e32 v2, v2
	v_mul_f32_e32 v1, v105, v1
	v_mul_f32_e32 v1, 0x3fb8aa3b, v1
	v_exp_f32_e32 v1, v1
	s_waitcnt lgkmcnt(0)
	v_lshlrev_b32_e32 v3, 16, v3
	v_mul_f32_e32 v2, v2, v3
	ds_read_u16 v3, v121
	v_fma_f32 v44, -v1, v1, 1.0
	v_max_f32_e32 v44, 0, v44
	v_sqrt_f32_e32 v44, v44
	s_waitcnt lgkmcnt(0)
	v_lshlrev_b32_e32 v3, 16, v3
	v_mul_f32_e32 v2, v2, v44
	ds_write2st64_b32 v110, v1, v2 offset0:108 offset1:173
	v_add_f32_e32 v1, v97, v46
	v_mul_f32_e32 v1, 0xbfb8aa3b, v1
	v_exp_f32_e32 v1, v1
	v_add_f32_e32 v2, v98, v50
	v_mul_f32_e32 v2, 0xbfb8aa3b, v2
	v_exp_f32_e32 v2, v2
	v_add_f32_e32 v1, 1.0, v1
	v_rcp_f32_e32 v1, v1
	v_add_f32_e32 v2, 1.0, v2
	v_rcp_f32_e32 v2, v2
	v_mul_f32_e32 v1, v105, v1
	v_mul_f32_e32 v1, 0x3fb8aa3b, v1
	v_exp_f32_e32 v1, v1
	v_mul_f32_e32 v2, v2, v3
	v_fma_f32 v44, -v1, v1, 1.0
	v_max_f32_e32 v44, 0, v44
	v_sqrt_f32_e32 v44, v44
	s_nop 0
	v_mul_f32_e32 v2, v2, v44
	ds_write_b32 v111, v1 offset:27648
	ds_write_b32 v111, v2 offset:44288
	v_add_f32_e32 v1, v97, v47
	v_mul_f32_e32 v1, 0xbfb8aa3b, v1
	v_exp_f32_e32 v1, v1
	v_add_f32_e32 v2, v98, v51
	v_mul_f32_e32 v2, 0xbfb8aa3b, v2
	v_exp_f32_e32 v2, v2
	v_add_f32_e32 v1, 1.0, v1
	v_rcp_f32_e32 v1, v1
	ds_read_u16 v3, v122
	v_add_f32_e32 v2, 1.0, v2
	v_rcp_f32_e32 v2, v2
	v_mul_f32_e32 v1, v105, v1
	v_mul_f32_e32 v1, 0x3fb8aa3b, v1
	v_exp_f32_e32 v1, v1
	s_waitcnt lgkmcnt(0)
	v_lshlrev_b32_e32 v3, 16, v3
	v_mul_f32_e32 v2, v2, v3
	ds_read_u16 v3, v124
	v_fma_f32 v44, -v1, v1, 1.0
	v_max_f32_e32 v44, 0, v44
	v_sqrt_f32_e32 v44, v44
	s_waitcnt lgkmcnt(0)
	v_lshlrev_b32_e32 v3, 16, v3
	v_mul_f32_e32 v2, v44, v2
	ds_write2st64_b32 v112, v1, v2 offset0:108 offset1:173
	ds_read_b128 v[48:51], v123 offset:18432
	ds_read_b128 v[44:47], v123 offset:9216
	s_waitcnt lgkmcnt(1)
	v_mfma_f32_16x16x32_bf16 v[52:55], v[40:43], v[48:51], 0
	ds_read_b128 v[48:51], v123 offset:9280
	s_waitcnt lgkmcnt(1)
	v_mfma_f32_16x16x32_bf16 v[44:47], v[40:43], v[44:47], 0
	s_waitcnt lgkmcnt(0)
	v_mfma_f32_16x16x32_bf16 v[48:51], v[36:39], v[48:51], v[44:47]
	s_nop 5
	ds_read_b128 v[44:47], v123 offset:18496
	s_nop 0
	v_add_f32_e32 v1, v99, v48
	v_mul_f32_e32 v1, 0xbfb8aa3b, v1
	v_exp_f32_e32 v1, v1
	s_waitcnt lgkmcnt(0)
	v_mfma_f32_16x16x32_bf16 v[44:47], v[36:39], v[44:47], v[52:55]
	v_add_f32_e32 v1, 1.0, v1
	v_rcp_f32_e32 v1, v1
	s_nop 0
	v_mul_f32_e32 v1, v106, v1
	s_nop 3
	v_add_f32_e32 v2, v100, v44
	v_mul_f32_e32 v2, 0xbfb8aa3b, v2
	v_mul_f32_e32 v1, 0x3fb8aa3b, v1
	v_exp_f32_e32 v2, v2
	v_exp_f32_e32 v1, v1
	v_add_f32_e32 v2, 1.0, v2
	v_fma_f32 v44, -v1, v1, 1.0
	v_rcp_f32_e32 v2, v2
	v_max_f32_e32 v44, 0, v44
	v_sqrt_f32_e32 v44, v44
	v_mul_f32_e32 v2, v2, v3
	v_mul_f32_e32 v2, v2, v44
	ds_write_b32 v109, v1 offset:27712
	ds_write_b32 v109, v2 offset:44352
	v_add_f32_e32 v1, v99, v49
	v_mul_f32_e32 v1, 0xbfb8aa3b, v1
	v_exp_f32_e32 v1, v1
	v_add_f32_e32 v2, v100, v45
	v_mul_f32_e32 v2, 0xbfb8aa3b, v2
	v_exp_f32_e32 v2, v2
	v_add_f32_e32 v1, 1.0, v1
	v_rcp_f32_e32 v1, v1
	ds_read_u16 v3, v125
	v_add_f32_e32 v2, 1.0, v2
	v_rcp_f32_e32 v2, v2
	v_mul_f32_e32 v1, v106, v1
	v_mul_f32_e32 v1, 0x3fb8aa3b, v1
	v_exp_f32_e32 v1, v1
	s_waitcnt lgkmcnt(0)
	v_lshlrev_b32_e32 v3, 16, v3
	v_mul_f32_e32 v2, v2, v3
	v_fma_f32 v44, -v1, v1, 1.0
	v_max_f32_e32 v44, 0, v44
	v_sqrt_f32_e32 v44, v44
	s_nop 0
	v_mul_f32_e32 v2, v2, v44
	ds_write_b32 v113, v1 offset:27712
	ds_write_b32 v113, v2 offset:44352
	v_add_f32_e32 v1, v99, v50
	v_mul_f32_e32 v1, 0xbfb8aa3b, v1
	v_exp_f32_e32 v1, v1
	v_add_f32_e32 v2, v100, v46
	v_mul_f32_e32 v2, 0xbfb8aa3b, v2
	v_exp_f32_e32 v2, v2
	v_add_f32_e32 v1, 1.0, v1
	v_rcp_f32_e32 v1, v1
	ds_read_u16 v3, v126
	v_add_f32_e32 v2, 1.0, v2
	v_rcp_f32_e32 v2, v2
	v_mul_f32_e32 v1, v106, v1
	v_mul_f32_e32 v1, 0x3fb8aa3b, v1
	v_exp_f32_e32 v1, v1
	s_waitcnt lgkmcnt(0)
	v_lshlrev_b32_e32 v3, 16, v3
	v_mul_f32_e32 v2, v2, v3
	v_fma_f32 v44, -v1, v1, 1.0
	v_max_f32_e32 v44, 0, v44
	v_sqrt_f32_e32 v44, v44
	s_nop 0
	v_mul_f32_e32 v2, v2, v44
	ds_write_b32 v111, v1 offset:27712
	ds_write_b32 v111, v2 offset:44352
	v_add_f32_e32 v1, v99, v51
	v_mul_f32_e32 v1, 0xbfb8aa3b, v1
	v_exp_f32_e32 v1, v1
	ds_read_u16 v3, v127
	v_add_f32_e32 v1, 1.0, v1
	v_rcp_f32_e32 v2, v1
	v_add_f32_e32 v1, v100, v47
	v_mul_f32_e32 v1, 0xbfb8aa3b, v1
	v_exp_f32_e32 v1, v1
	v_mul_f32_e32 v2, v106, v2
	v_mul_f32_e32 v2, 0x3fb8aa3b, v2
	v_exp_f32_e32 v2, v2
	v_add_f32_e32 v1, 1.0, v1
	v_rcp_f32_e32 v1, v1
	s_waitcnt lgkmcnt(0)
	v_lshlrev_b32_e32 v3, 16, v3
	v_fma_f32 v44, -v2, v2, 1.0
	v_max_f32_e32 v44, 0, v44
	v_sqrt_f32_e32 v44, v44
	v_mul_f32_e32 v1, v1, v3
	v_mul_f32_e32 v1, v44, v1
	ds_write_b32 v114, v2 offset:27712
	ds_write_b32 v114, v1 offset:44352
	ds_read_b128 v[44:47], v128 offset:9216
	ds_read_b128 v[52:55], v128 offset:9280
	s_waitcnt lgkmcnt(1)
	v_mfma_f32_16x16x32_bf16 v[44:47], v[40:43], v[44:47], 0
	ds_read_b128 v[48:51], v128 offset:18432
	ds_read_u16 v3, v129
	s_waitcnt lgkmcnt(0)
	v_lshlrev_b32_e32 v3, 16, v3
	v_mfma_f32_16x16x32_bf16 v[44:47], v[36:39], v[52:55], v[44:47]
	ds_read_b128 v[52:55], v128 offset:18496
	v_mfma_f32_16x16x32_bf16 v[48:51], v[40:43], v[48:51], 0
	s_waitcnt lgkmcnt(0)
	v_mfma_f32_16x16x32_bf16 v[48:51], v[36:39], v[52:55], v[48:51]
	s_nop 3
	v_add_f32_e32 v1, v101, v44
	v_mul_f32_e32 v1, 0xbfb8aa3b, v1
	v_exp_f32_e32 v1, v1
	s_nop 0
	v_add_f32_e32 v1, 1.0, v1
	v_rcp_f32_e32 v1, v1
	v_add_f32_e32 v2, v102, v48
	v_mul_f32_e32 v2, 0xbfb8aa3b, v2
	v_exp_f32_e32 v2, v2
	v_mul_f32_e32 v1, v107, v1
	v_mul_f32_e32 v1, 0x3fb8aa3b, v1
	v_exp_f32_e32 v1, v1
	v_add_f32_e32 v2, 1.0, v2
	v_rcp_f32_e32 v2, v2
	v_fma_f32 v44, -v1, v1, 1.0
	v_max_f32_e32 v44, 0, v44
	v_sqrt_f32_e32 v44, v44
	v_mul_f32_e32 v2, v2, v3
	v_mul_f32_e32 v2, v2, v44
	ds_write_b32 v109, v1 offset:27776
	ds_write_b32 v109, v2 offset:44416
	v_add_f32_e32 v1, v101, v45
	v_mul_f32_e32 v1, 0xbfb8aa3b, v1
	v_exp_f32_e32 v1, v1
	v_add_f32_e32 v2, v102, v49
	v_mul_f32_e32 v2, 0xbfb8aa3b, v2
	v_exp_f32_e32 v2, v2
	v_add_f32_e32 v1, 1.0, v1
	v_rcp_f32_e32 v1, v1
	ds_read_u16 v3, v130
	v_add_f32_e32 v2, 1.0, v2
	v_rcp_f32_e32 v2, v2
	v_mul_f32_e32 v1, v107, v1
	v_mul_f32_e32 v1, 0x3fb8aa3b, v1
	v_exp_f32_e32 v1, v1
	s_waitcnt lgkmcnt(0)
	v_lshlrev_b32_e32 v3, 16, v3
	v_mul_f32_e32 v2, v2, v3
	v_fma_f32 v44, -v1, v1, 1.0
	v_max_f32_e32 v44, 0, v44
	v_sqrt_f32_e32 v44, v44
	s_nop 0
	v_mul_f32_e32 v2, v2, v44
	ds_write_b32 v113, v1 offset:27776
	ds_write_b32 v113, v2 offset:44416
	v_add_f32_e32 v1, v101, v46
	v_mul_f32_e32 v1, 0xbfb8aa3b, v1
	v_exp_f32_e32 v1, v1
	v_add_f32_e32 v2, v102, v50
	v_mul_f32_e32 v2, 0xbfb8aa3b, v2
	v_exp_f32_e32 v2, v2
	v_add_f32_e32 v1, 1.0, v1
	v_rcp_f32_e32 v1, v1
	ds_read_u16 v3, v131
	v_add_f32_e32 v2, 1.0, v2
	v_rcp_f32_e32 v2, v2
	v_mul_f32_e32 v1, v107, v1
	v_mul_f32_e32 v1, 0x3fb8aa3b, v1
	v_exp_f32_e32 v1, v1
	s_waitcnt lgkmcnt(0)
	v_lshlrev_b32_e32 v3, 16, v3
	v_mul_f32_e32 v2, v2, v3
	v_fma_f32 v44, -v1, v1, 1.0
	v_max_f32_e32 v44, 0, v44
	v_sqrt_f32_e32 v44, v44
	s_nop 0
	v_mul_f32_e32 v2, v2, v44
	ds_write_b32 v111, v1 offset:27776
	ds_write_b32 v111, v2 offset:44416
	v_add_f32_e32 v1, v101, v47
	v_mul_f32_e32 v1, 0xbfb8aa3b, v1
	v_exp_f32_e32 v1, v1
	v_add_f32_e32 v2, v102, v51
	v_mul_f32_e32 v2, 0xbfb8aa3b, v2
	v_exp_f32_e32 v2, v2
	v_add_f32_e32 v1, 1.0, v1
	v_rcp_f32_e32 v1, v1
	ds_read_u16 v3, v132
	v_add_f32_e32 v2, 1.0, v2
	v_rcp_f32_e32 v2, v2
	v_mul_f32_e32 v1, v107, v1
	v_mul_f32_e32 v1, 0x3fb8aa3b, v1
	v_exp_f32_e32 v1, v1
	s_waitcnt lgkmcnt(0)
	v_lshlrev_b32_e32 v3, 16, v3
	v_mul_f32_e32 v2, v2, v3
	v_fma_f32 v44, -v1, v1, 1.0
	v_max_f32_e32 v44, 0, v44
	v_sqrt_f32_e32 v44, v44
	s_nop 0
	v_mul_f32_e32 v2, v44, v2
	ds_write_b32 v114, v1 offset:27776
	ds_write_b32 v114, v2 offset:44416
	ds_read_b128 v[44:47], v133 offset:9216
	ds_read_b128 v[48:51], v133 offset:18432
	s_waitcnt lgkmcnt(1)
	v_mfma_f32_16x16x32_bf16 v[44:47], v[40:43], v[44:47], 0
	ds_read_u16 v3, v134
	s_waitcnt lgkmcnt(0)
	v_lshlrev_b32_e32 v3, 16, v3
	v_mfma_f32_16x16x32_bf16 v[48:51], v[40:43], v[48:51], 0
	ds_read_b128 v[40:43], v133 offset:9280
	s_waitcnt lgkmcnt(0)
	v_mfma_f32_16x16x32_bf16 v[40:43], v[36:39], v[40:43], v[44:47]
	s_nop 2
	ds_read_b128 v[44:47], v133 offset:18496
	s_waitcnt lgkmcnt(0)
	v_mfma_f32_16x16x32_bf16 v[36:39], v[36:39], v[44:47], v[48:51]
	s_nop 1
	v_add_f32_e32 v1, v103, v40
	v_mul_f32_e32 v1, 0xbfb8aa3b, v1
	v_exp_f32_e32 v1, v1
	s_nop 2
	v_add_f32_e32 v2, v104, v36
	v_mul_f32_e32 v2, 0xbfb8aa3b, v2
	v_exp_f32_e32 v2, v2
	v_add_f32_e32 v1, 1.0, v1
	v_rcp_f32_e32 v1, v1
	v_add_f32_e32 v2, 1.0, v2
	v_rcp_f32_e32 v2, v2
	v_mul_f32_e32 v1, v108, v1
	v_mul_f32_e32 v1, 0x3fb8aa3b, v1
	v_exp_f32_e32 v1, v1
	v_mul_f32_e32 v2, v2, v3
	v_fma_f32 v36, -v1, v1, 1.0
	v_max_f32_e32 v36, 0, v36
	v_sqrt_f32_e32 v36, v36
	s_nop 0
	v_mul_f32_e32 v2, v2, v36
	ds_write_b32 v109, v1 offset:27840
	ds_write_b32 v109, v2 offset:44480
	v_add_f32_e32 v1, v103, v41
	v_mul_f32_e32 v1, 0xbfb8aa3b, v1
	v_exp_f32_e32 v1, v1
	v_add_f32_e32 v2, v104, v37
	v_mul_f32_e32 v2, 0xbfb8aa3b, v2
	v_exp_f32_e32 v2, v2
	v_add_f32_e32 v1, 1.0, v1
	v_rcp_f32_e32 v1, v1
	ds_read_u16 v3, v135
	v_add_f32_e32 v2, 1.0, v2
	v_rcp_f32_e32 v2, v2
	v_mul_f32_e32 v1, v108, v1
	v_mul_f32_e32 v1, 0x3fb8aa3b, v1
	v_exp_f32_e32 v1, v1
	s_waitcnt lgkmcnt(0)
	v_lshlrev_b32_e32 v3, 16, v3
	v_mul_f32_e32 v2, v2, v3
	v_fma_f32 v36, -v1, v1, 1.0
	v_max_f32_e32 v36, 0, v36
	v_sqrt_f32_e32 v36, v36
	s_nop 0
	v_mul_f32_e32 v2, v2, v36
	ds_write_b32 v113, v1 offset:27840
	ds_write_b32 v113, v2 offset:44480
	v_add_f32_e32 v1, v103, v42
	v_mul_f32_e32 v1, 0xbfb8aa3b, v1
	v_exp_f32_e32 v1, v1
	v_add_f32_e32 v2, v104, v38
	v_mul_f32_e32 v2, 0xbfb8aa3b, v2
	v_exp_f32_e32 v2, v2
	v_add_f32_e32 v1, 1.0, v1
	v_rcp_f32_e32 v1, v1
	ds_read_u16 v3, v136
	v_add_f32_e32 v2, 1.0, v2
	v_rcp_f32_e32 v2, v2
	v_mul_f32_e32 v1, v108, v1
	v_mul_f32_e32 v1, 0x3fb8aa3b, v1
	v_exp_f32_e32 v1, v1
	s_waitcnt lgkmcnt(0)
	v_lshlrev_b32_e32 v3, 16, v3
	v_mul_f32_e32 v2, v2, v3
	v_fma_f32 v36, -v1, v1, 1.0
	v_max_f32_e32 v36, 0, v36
	v_sqrt_f32_e32 v36, v36
	s_nop 0
	v_mul_f32_e32 v2, v2, v36
	ds_write_b32 v111, v1 offset:27840
	ds_write_b32 v111, v2 offset:44480
	v_add_f32_e32 v1, v103, v43
	v_mul_f32_e32 v1, 0xbfb8aa3b, v1
	v_exp_f32_e32 v1, v1
	ds_read_u16 v3, v137
	v_add_f32_e32 v1, 1.0, v1
	v_rcp_f32_e32 v2, v1
	v_add_f32_e32 v1, v104, v39
	v_mul_f32_e32 v1, 0xbfb8aa3b, v1
	v_exp_f32_e32 v1, v1
	v_mul_f32_e32 v2, v108, v2
	v_mul_f32_e32 v2, 0x3fb8aa3b, v2
	v_exp_f32_e32 v2, v2
	v_add_f32_e32 v1, 1.0, v1
	v_rcp_f32_e32 v1, v1
	s_waitcnt lgkmcnt(0)
	v_lshlrev_b32_e32 v3, 16, v3
	v_fma_f32 v36, -v2, v2, 1.0
	v_max_f32_e32 v36, 0, v36
	v_sqrt_f32_e32 v36, v36
	v_mul_f32_e32 v1, v1, v3
	v_mul_f32_e32 v1, v36, v1
	ds_write_b32 v114, v2 offset:27840
	ds_write_b32 v114, v1 offset:44480
	s_waitcnt lgkmcnt(0)
	s_barrier
	s_and_saveexec_b64 s[20:21], s[4:5]
	s_cbranch_execz .LBB0_273
	s_and_b64 s[28:29], s[16:17], exec
	s_cselect_b32 s35, 0, 0x3ffc
	s_cselect_b32 s19, 1, -1
	s_mulk_i32 s19, 0x104
	v_and_b32_e32 v164, 0xff, v92
	v_lshl_add_u32 v164, v164, 2, s56
	v_add_u32_e32 v164, s35, v164
	s_lshl_b32 s23, s19, 3
	v_add_u32_e32 v165, s19, v164
	v_add_u32_e32 v166, s19, v165
	v_add_u32_e32 v167, s19, v166
	v_add_u32_e32 v168, s19, v167
	v_add_u32_e32 v169, s19, v168
	v_add_u32_e32 v170, s19, v169
	v_add_u32_e32 v171, s19, v170
	ds_read2st64_b32 v[148:149], v164 offset0:108 offset1:173
	ds_read2st64_b32 v[150:151], v165 offset0:108 offset1:173
	ds_read2st64_b32 v[152:153], v166 offset0:108 offset1:173
	ds_read2st64_b32 v[154:155], v167 offset0:108 offset1:173
	ds_read2st64_b32 v[156:157], v168 offset0:108 offset1:173
	ds_read2st64_b32 v[158:159], v169 offset0:108 offset1:173
	ds_read2st64_b32 v[160:161], v170 offset0:108 offset1:173
	ds_read2st64_b32 v[162:163], v171 offset0:108 offset1:173
	s_waitcnt lgkmcnt(7)
	v_fma_f32 v91, v91, v148, v149
	ds_write_b32 v164, v91 offset:44288
	v_add_u32_e32 v164, s23, v164
	ds_read2st64_b32 v[148:149], v164 offset0:108 offset1:173
	s_waitcnt lgkmcnt(8)
	v_fma_f32 v91, v91, v150, v151
	ds_write_b32 v165, v91 offset:44288
	v_add_u32_e32 v165, s23, v165
	ds_read2st64_b32 v[150:151], v165 offset0:108 offset1:173
	s_waitcnt lgkmcnt(9)
	v_fma_f32 v91, v91, v152, v153
	ds_write_b32 v166, v91 offset:44288
	v_add_u32_e32 v166, s23, v166
	ds_read2st64_b32 v[152:153], v166 offset0:108 offset1:173
	s_waitcnt lgkmcnt(10)
	v_fma_f32 v91, v91, v154, v155
	ds_write_b32 v167, v91 offset:44288
	v_add_u32_e32 v167, s23, v167
	ds_read2st64_b32 v[154:155], v167 offset0:108 offset1:173
	s_waitcnt lgkmcnt(11)
	v_fma_f32 v91, v91, v156, v157
	ds_write_b32 v168, v91 offset:44288
	v_add_u32_e32 v168, s23, v168
	ds_read2st64_b32 v[156:157], v168 offset0:108 offset1:173
	s_waitcnt lgkmcnt(12)
	v_fma_f32 v91, v91, v158, v159
	ds_write_b32 v169, v91 offset:44288
	v_add_u32_e32 v169, s23, v169
	ds_read2st64_b32 v[158:159], v169 offset0:108 offset1:173
	s_waitcnt lgkmcnt(13)
	v_fma_f32 v91, v91, v160, v161
	ds_write_b32 v170, v91 offset:44288
	v_add_u32_e32 v170, s23, v170
	ds_read2st64_b32 v[160:161], v170 offset0:108 offset1:173
	s_waitcnt lgkmcnt(14)
	v_fma_f32 v91, v91, v162, v163
	ds_write_b32 v171, v91 offset:44288
	v_add_u32_e32 v171, s23, v171
	ds_read2st64_b32 v[162:163], v171 offset0:108 offset1:173
	s_mov_b32 s18, 7
.Lscan_p:
	s_waitcnt lgkmcnt(14)
	v_fma_f32 v91, v91, v148, v149
	ds_write_b32 v164, v91 offset:44288
	v_add_u32_e32 v164, s23, v164
	ds_read2st64_b32 v[148:149], v164 offset0:108 offset1:173
	s_waitcnt lgkmcnt(14)
	v_fma_f32 v91, v91, v150, v151
	ds_write_b32 v165, v91 offset:44288
	v_add_u32_e32 v165, s23, v165
	ds_read2st64_b32 v[150:151], v165 offset0:108 offset1:173
	s_waitcnt lgkmcnt(14)
	v_fma_f32 v91, v91, v152, v153
	ds_write_b32 v166, v91 offset:44288
	v_add_u32_e32 v166, s23, v166
	ds_read2st64_b32 v[152:153], v166 offset0:108 offset1:173
	s_waitcnt lgkmcnt(14)
	v_fma_f32 v91, v91, v154, v155
	ds_write_b32 v167, v91 offset:44288
	v_add_u32_e32 v167, s23, v167
	ds_read2st64_b32 v[154:155], v167 offset0:108 offset1:173
	s_waitcnt lgkmcnt(14)
	v_fma_f32 v91, v91, v156, v157
	ds_write_b32 v168, v91 offset:44288
	v_add_u32_e32 v168, s23, v168
	ds_read2st64_b32 v[156:157], v168 offset0:108 offset1:173
	s_waitcnt lgkmcnt(14)
	v_fma_f32 v91, v91, v158, v159
	ds_write_b32 v169, v91 offset:44288
	v_add_u32_e32 v169, s23, v169
	ds_read2st64_b32 v[158:159], v169 offset0:108 offset1:173
	s_waitcnt lgkmcnt(14)
	v_fma_f32 v91, v91, v160, v161
	ds_write_b32 v170, v91 offset:44288
	v_add_u32_e32 v170, s23, v170
	ds_read2st64_b32 v[160:161], v170 offset0:108 offset1:173
	s_waitcnt lgkmcnt(14)
	v_fma_f32 v91, v91, v162, v163
	ds_write_b32 v171, v91 offset:44288
	v_add_u32_e32 v171, s23, v171
	ds_read2st64_b32 v[162:163], v171 offset0:108 offset1:173
	s_add_i32 s18, s18, -1
	s_cmp_lg_u32 s18, 0
	s_cbranch_scc1 .Lscan_p

.LBB0_305:
	s_waitcnt lgkmcnt(0)
	s_barrier
	ds_read_b128 v[40:43], v117
	ds_read_b128 v[36:39], v117 offset:64
	ds_read_b128 v[44:47], v118 offset:9216
	ds_read_b128 v[48:51], v118 offset:18432
	ds_read_b128 v[52:55], v118 offset:9280
	s_waitcnt lgkmcnt(2)
	v_mfma_f32_16x16x32_bf16 v[44:47], v[40:43], v[44:47], 0
	ds_read_u16 v3, v119
	s_waitcnt lgkmcnt(0)
	v_lshlrev_b32_e32 v3, 16, v3
	v_mfma_f32_16x16x32_bf16 v[44:47], v[36:39], v[52:55], v[44:47]
	ds_read_b128 v[52:55], v118 offset:18496
	v_mfma_f32_16x16x32_bf16 v[48:51], v[40:43], v[48:51], 0
	s_waitcnt lgkmcnt(0)
	v_mfma_f32_16x16x32_bf16 v[48:51], v[36:39], v[52:55], v[48:51]
	s_nop 3
	v_add_f32_e32 v1, v97, v44
	v_mul_f32_e32 v1, 0xbfb8aa3b, v1
	v_exp_f32_e32 v1, v1
	s_nop 0
	v_add_f32_e32 v1, 1.0, v1
	v_rcp_f32_e32 v1, v1
	v_add_f32_e32 v2, v98, v48
	v_mul_f32_e32 v2, 0xbfb8aa3b, v2
	v_exp_f32_e32 v2, v2
	v_mul_f32_e32 v1, v105, v1
	v_mul_f32_e32 v1, 0x3fb8aa3b, v1
	v_exp_f32_e32 v1, v1
	v_add_f32_e32 v2, 1.0, v2
	v_rcp_f32_e32 v2, v2
	v_fma_f32 v44, -v1, v1, 1.0
	v_max_f32_e32 v44, 0, v44
	v_sqrt_f32_e32 v44, v44
	v_mul_f32_e32 v2, v2, v3
	v_mul_f32_e32 v2, v2, v44
	ds_write_b32 v109, v1 offset:27648
	ds_write_b32 v109, v2 offset:44288
	v_add_f32_e32 v1, v97, v45
	v_mul_f32_e32 v1, 0xbfb8aa3b, v1
	v_exp_f32_e32 v1, v1
	v_add_f32_e32 v2, v98, v49
	v_mul_f32_e32 v2, 0xbfb8aa3b, v2
	v_exp_f32_e32 v2, v2
	v_add_f32_e32 v1, 1.0, v1
	v_rcp_f32_e32 v1, v1
	ds_read_u16 v3, v120
	v_add_f32_e32 v2, 1.0, v2
	v_rcp_f32_e32 v2, v2
	v_mul_f32_e32 v1, v105, v1
	v_mul_f32_e32 v1, 0x3fb8aa3b, v1
	v_exp_f32_e32 v1, v1
	s_waitcnt lgkmcnt(0)
	v_lshlrev_b32_e32 v3, 16, v3
	v_mul_f32_e32 v2, v2, v3
	ds_read_u16 v3, v121
	v_fma_f32 v44, -v1, v1, 1.0
	v_max_f32_e32 v44, 0, v44
	v_sqrt_f32_e32 v44, v44
	s_waitcnt lgkmcnt(0)
	v_lshlrev_b32_e32 v3, 16, v3
	v_mul_f32_e32 v2, v2, v44
	ds_write2st64_b32 v110, v1, v2 offset0:108 offset1:173
	v_add_f32_e32 v1, v97, v46
	v_mul_f32_e32 v1, 0xbfb8aa3b, v1
	v_exp_f32_e32 v1, v1
	v_add_f32_e32 v2, v98, v50
	v_mul_f32_e32 v2, 0xbfb8aa3b, v2
	v_exp_f32_e32 v2, v2
	v_add_f32_e32 v1, 1.0, v1
	v_rcp_f32_e32 v1, v1
	v_add_f32_e32 v2, 1.0, v2
	v_rcp_f32_e32 v2, v2
	v_mul_f32_e32 v1, v105, v1
	v_mul_f32_e32 v1, 0x3fb8aa3b, v1
	v_exp_f32_e32 v1, v1
	v_mul_f32_e32 v2, v2, v3
	v_fma_f32 v44, -v1, v1, 1.0
	v_max_f32_e32 v44, 0, v44
	v_sqrt_f32_e32 v44, v44
	s_nop 0
	v_mul_f32_e32 v2, v2, v44
	ds_write_b32 v111, v1 offset:27648
	ds_write_b32 v111, v2 offset:44288
	v_add_f32_e32 v1, v97, v47
	v_mul_f32_e32 v1, 0xbfb8aa3b, v1
	v_exp_f32_e32 v1, v1
	v_add_f32_e32 v2, v98, v51
	v_mul_f32_e32 v2, 0xbfb8aa3b, v2
	v_exp_f32_e32 v2, v2
	v_add_f32_e32 v1, 1.0, v1
	v_rcp_f32_e32 v1, v1
	ds_read_u16 v3, v122
	v_add_f32_e32 v2, 1.0, v2
	v_rcp_f32_e32 v2, v2
	v_mul_f32_e32 v1, v105, v1
	v_mul_f32_e32 v1, 0x3fb8aa3b, v1
	v_exp_f32_e32 v1, v1
	s_waitcnt lgkmcnt(0)
	v_lshlrev_b32_e32 v3, 16, v3
	v_mul_f32_e32 v2, v2, v3
	ds_read_u16 v3, v124
	v_fma_f32 v44, -v1, v1, 1.0
	v_max_f32_e32 v44, 0, v44
	v_sqrt_f32_e32 v44, v44
	s_waitcnt lgkmcnt(0)
	v_lshlrev_b32_e32 v3, 16, v3
	v_mul_f32_e32 v2, v44, v2
	ds_write2st64_b32 v112, v1, v2 offset0:108 offset1:173
	ds_read_b128 v[48:51], v123 offset:18432
	ds_read_b128 v[44:47], v123 offset:9216
	s_waitcnt lgkmcnt(1)
	v_mfma_f32_16x16x32_bf16 v[52:55], v[40:43], v[48:51], 0
	ds_read_b128 v[48:51], v123 offset:9280
	s_waitcnt lgkmcnt(1)
	v_mfma_f32_16x16x32_bf16 v[44:47], v[40:43], v[44:47], 0
	s_waitcnt lgkmcnt(0)
	v_mfma_f32_16x16x32_bf16 v[48:51], v[36:39], v[48:51], v[44:47]
	s_nop 5
	ds_read_b128 v[44:47], v123 offset:18496
	s_nop 0
	v_add_f32_e32 v1, v99, v48
	v_mul_f32_e32 v1, 0xbfb8aa3b, v1
	v_exp_f32_e32 v1, v1
	s_waitcnt lgkmcnt(0)
	v_mfma_f32_16x16x32_bf16 v[44:47], v[36:39], v[44:47], v[52:55]
	v_add_f32_e32 v1, 1.0, v1
	v_rcp_f32_e32 v1, v1
	s_nop 0
	v_mul_f32_e32 v1, v106, v1
	s_nop 3
	v_add_f32_e32 v2, v100, v44
	v_mul_f32_e32 v2, 0xbfb8aa3b, v2
	v_mul_f32_e32 v1, 0x3fb8aa3b, v1
	v_exp_f32_e32 v2, v2
	v_exp_f32_e32 v1, v1
	v_add_f32_e32 v2, 1.0, v2
	v_fma_f32 v44, -v1, v1, 1.0
	v_rcp_f32_e32 v2, v2
	v_max_f32_e32 v44, 0, v44
	v_sqrt_f32_e32 v44, v44
	v_mul_f32_e32 v2, v2, v3
	v_mul_f32_e32 v2, v2, v44
	ds_write_b32 v109, v1 offset:27712
	ds_write_b32 v109, v2 offset:44352
	v_add_f32_e32 v1, v99, v49
	v_mul_f32_e32 v1, 0xbfb8aa3b, v1
	v_exp_f32_e32 v1, v1
	v_add_f32_e32 v2, v100, v45
	v_mul_f32_e32 v2, 0xbfb8aa3b, v2
	v_exp_f32_e32 v2, v2
	v_add_f32_e32 v1, 1.0, v1
	v_rcp_f32_e32 v1, v1
	ds_read_u16 v3, v125
	v_add_f32_e32 v2, 1.0, v2
	v_rcp_f32_e32 v2, v2
	v_mul_f32_e32 v1, v106, v1
	v_mul_f32_e32 v1, 0x3fb8aa3b, v1
	v_exp_f32_e32 v1, v1
	s_waitcnt lgkmcnt(0)
	v_lshlrev_b32_e32 v3, 16, v3
	v_mul_f32_e32 v2, v2, v3
	v_fma_f32 v44, -v1, v1, 1.0
	v_max_f32_e32 v44, 0, v44
	v_sqrt_f32_e32 v44, v44
	s_nop 0
	v_mul_f32_e32 v2, v2, v44
	ds_write_b32 v113, v1 offset:27712
	ds_write_b32 v113, v2 offset:44352
	v_add_f32_e32 v1, v99, v50
	v_mul_f32_e32 v1, 0xbfb8aa3b, v1
	v_exp_f32_e32 v1, v1
	v_add_f32_e32 v2, v100, v46
	v_mul_f32_e32 v2, 0xbfb8aa3b, v2
	v_exp_f32_e32 v2, v2
	v_add_f32_e32 v1, 1.0, v1
	v_rcp_f32_e32 v1, v1
	ds_read_u16 v3, v126
	v_add_f32_e32 v2, 1.0, v2
	v_rcp_f32_e32 v2, v2
	v_mul_f32_e32 v1, v106, v1
	v_mul_f32_e32 v1, 0x3fb8aa3b, v1
	v_exp_f32_e32 v1, v1
	s_waitcnt lgkmcnt(0)
	v_lshlrev_b32_e32 v3, 16, v3
	v_mul_f32_e32 v2, v2, v3
	v_fma_f32 v44, -v1, v1, 1.0
	v_max_f32_e32 v44, 0, v44
	v_sqrt_f32_e32 v44, v44
	s_nop 0
	v_mul_f32_e32 v2, v2, v44
	ds_write_b32 v111, v1 offset:27712
	ds_write_b32 v111, v2 offset:44352
	v_add_f32_e32 v1, v99, v51
	v_mul_f32_e32 v1, 0xbfb8aa3b, v1
	v_exp_f32_e32 v1, v1
	ds_read_u16 v3, v127
	v_add_f32_e32 v1, 1.0, v1
	v_rcp_f32_e32 v2, v1
	v_add_f32_e32 v1, v100, v47
	v_mul_f32_e32 v1, 0xbfb8aa3b, v1
	v_exp_f32_e32 v1, v1
	v_mul_f32_e32 v2, v106, v2
	v_mul_f32_e32 v2, 0x3fb8aa3b, v2
	v_exp_f32_e32 v2, v2
	v_add_f32_e32 v1, 1.0, v1
	v_rcp_f32_e32 v1, v1
	s_waitcnt lgkmcnt(0)
	v_lshlrev_b32_e32 v3, 16, v3
	v_fma_f32 v44, -v2, v2, 1.0
	v_max_f32_e32 v44, 0, v44
	v_sqrt_f32_e32 v44, v44
	v_mul_f32_e32 v1, v1, v3
	v_mul_f32_e32 v1, v44, v1
	ds_write_b32 v114, v2 offset:27712
	ds_write_b32 v114, v1 offset:44352
	ds_read_b128 v[44:47], v128 offset:9216
	ds_read_b128 v[52:55], v128 offset:9280
	s_waitcnt lgkmcnt(1)
	v_mfma_f32_16x16x32_bf16 v[44:47], v[40:43], v[44:47], 0
	ds_read_b128 v[48:51], v128 offset:18432
	ds_read_u16 v3, v129
	s_waitcnt lgkmcnt(0)
	v_lshlrev_b32_e32 v3, 16, v3
	v_mfma_f32_16x16x32_bf16 v[44:47], v[36:39], v[52:55], v[44:47]
	ds_read_b128 v[52:55], v128 offset:18496
	v_mfma_f32_16x16x32_bf16 v[48:51], v[40:43], v[48:51], 0
	s_waitcnt lgkmcnt(0)
	v_mfma_f32_16x16x32_bf16 v[48:51], v[36:39], v[52:55], v[48:51]
	s_nop 3
	v_add_f32_e32 v1, v101, v44
	v_mul_f32_e32 v1, 0xbfb8aa3b, v1
	v_exp_f32_e32 v1, v1
	s_nop 0
	v_add_f32_e32 v1, 1.0, v1
	v_rcp_f32_e32 v1, v1
	v_add_f32_e32 v2, v102, v48
	v_mul_f32_e32 v2, 0xbfb8aa3b, v2
	v_exp_f32_e32 v2, v2
	v_mul_f32_e32 v1, v107, v1
	v_mul_f32_e32 v1, 0x3fb8aa3b, v1
	v_exp_f32_e32 v1, v1
	v_add_f32_e32 v2, 1.0, v2
	v_rcp_f32_e32 v2, v2
	v_fma_f32 v44, -v1, v1, 1.0
	v_max_f32_e32 v44, 0, v44
	v_sqrt_f32_e32 v44, v44
	v_mul_f32_e32 v2, v2, v3
	v_mul_f32_e32 v2, v2, v44
	ds_write_b32 v109, v1 offset:27776
	ds_write_b32 v109, v2 offset:44416
	v_add_f32_e32 v1, v101, v45
	v_mul_f32_e32 v1, 0xbfb8aa3b, v1
	v_exp_f32_e32 v1, v1
	v_add_f32_e32 v2, v102, v49
	v_mul_f32_e32 v2, 0xbfb8aa3b, v2
	v_exp_f32_e32 v2, v2
	v_add_f32_e32 v1, 1.0, v1
	v_rcp_f32_e32 v1, v1
	ds_read_u16 v3, v130
	v_add_f32_e32 v2, 1.0, v2
	v_rcp_f32_e32 v2, v2
	v_mul_f32_e32 v1, v107, v1
	v_mul_f32_e32 v1, 0x3fb8aa3b, v1
	v_exp_f32_e32 v1, v1
	s_waitcnt lgkmcnt(0)
	v_lshlrev_b32_e32 v3, 16, v3
	v_mul_f32_e32 v2, v2, v3
	v_fma_f32 v44, -v1, v1, 1.0
	v_max_f32_e32 v44, 0, v44
	v_sqrt_f32_e32 v44, v44
	s_nop 0
	v_mul_f32_e32 v2, v2, v44
	ds_write_b32 v113, v1 offset:27776
	ds_write_b32 v113, v2 offset:44416
	v_add_f32_e32 v1, v101, v46
	v_mul_f32_e32 v1, 0xbfb8aa3b, v1
	v_exp_f32_e32 v1, v1
	v_add_f32_e32 v2, v102, v50
	v_mul_f32_e32 v2, 0xbfb8aa3b, v2
	v_exp_f32_e32 v2, v2
	v_add_f32_e32 v1, 1.0, v1
	v_rcp_f32_e32 v1, v1
	ds_read_u16 v3, v131
	v_add_f32_e32 v2, 1.0, v2
	v_rcp_f32_e32 v2, v2
	v_mul_f32_e32 v1, v107, v1
	v_mul_f32_e32 v1, 0x3fb8aa3b, v1
	v_exp_f32_e32 v1, v1
	s_waitcnt lgkmcnt(0)
	v_lshlrev_b32_e32 v3, 16, v3
	v_mul_f32_e32 v2, v2, v3
	v_fma_f32 v44, -v1, v1, 1.0
	v_max_f32_e32 v44, 0, v44
	v_sqrt_f32_e32 v44, v44
	s_nop 0
	v_mul_f32_e32 v2, v2, v44
	ds_write_b32 v111, v1 offset:27776
	ds_write_b32 v111, v2 offset:44416
	v_add_f32_e32 v1, v101, v47
	v_mul_f32_e32 v1, 0xbfb8aa3b, v1
	v_exp_f32_e32 v1, v1
	v_add_f32_e32 v2, v102, v51
	v_mul_f32_e32 v2, 0xbfb8aa3b, v2
	v_exp_f32_e32 v2, v2
	v_add_f32_e32 v1, 1.0, v1
	v_rcp_f32_e32 v1, v1
	ds_read_u16 v3, v132
	v_add_f32_e32 v2, 1.0, v2
	v_rcp_f32_e32 v2, v2
	v_mul_f32_e32 v1, v107, v1
	v_mul_f32_e32 v1, 0x3fb8aa3b, v1
	v_exp_f32_e32 v1, v1
	s_waitcnt lgkmcnt(0)
	v_lshlrev_b32_e32 v3, 16, v3
	v_mul_f32_e32 v2, v2, v3
	v_fma_f32 v44, -v1, v1, 1.0
	v_max_f32_e32 v44, 0, v44
	v_sqrt_f32_e32 v44, v44
	s_nop 0
	v_mul_f32_e32 v2, v44, v2
	ds_write_b32 v114, v1 offset:27776
	ds_write_b32 v114, v2 offset:44416
	ds_read_b128 v[44:47], v133 offset:9216
	ds_read_b128 v[48:51], v133 offset:18432
	s_waitcnt lgkmcnt(1)
	v_mfma_f32_16x16x32_bf16 v[44:47], v[40:43], v[44:47], 0
	ds_read_u16 v3, v134
	s_waitcnt lgkmcnt(0)
	v_lshlrev_b32_e32 v3, 16, v3
	v_mfma_f32_16x16x32_bf16 v[48:51], v[40:43], v[48:51], 0
	ds_read_b128 v[40:43], v133 offset:9280
	s_waitcnt lgkmcnt(0)
	v_mfma_f32_16x16x32_bf16 v[40:43], v[36:39], v[40:43], v[44:47]
	s_nop 2
	ds_read_b128 v[44:47], v133 offset:18496
	s_waitcnt lgkmcnt(0)
	v_mfma_f32_16x16x32_bf16 v[36:39], v[36:39], v[44:47], v[48:51]
	s_nop 1
	v_add_f32_e32 v1, v103, v40
	v_mul_f32_e32 v1, 0xbfb8aa3b, v1
	v_exp_f32_e32 v1, v1
	s_nop 2
	v_add_f32_e32 v2, v104, v36
	v_mul_f32_e32 v2, 0xbfb8aa3b, v2
	v_exp_f32_e32 v2, v2
	v_add_f32_e32 v1, 1.0, v1
	v_rcp_f32_e32 v1, v1
	v_add_f32_e32 v2, 1.0, v2
	v_rcp_f32_e32 v2, v2
	v_mul_f32_e32 v1, v108, v1
	v_mul_f32_e32 v1, 0x3fb8aa3b, v1
	v_exp_f32_e32 v1, v1
	v_mul_f32_e32 v2, v2, v3
	v_fma_f32 v36, -v1, v1, 1.0
	v_max_f32_e32 v36, 0, v36
	v_sqrt_f32_e32 v36, v36
	s_nop 0
	v_mul_f32_e32 v2, v2, v36
	ds_write_b32 v109, v1 offset:27840
	ds_write_b32 v109, v2 offset:44480
	v_add_f32_e32 v1, v103, v41
	v_mul_f32_e32 v1, 0xbfb8aa3b, v1
	v_exp_f32_e32 v1, v1
	v_add_f32_e32 v2, v104, v37
	v_mul_f32_e32 v2, 0xbfb8aa3b, v2
	v_exp_f32_e32 v2, v2
	v_add_f32_e32 v1, 1.0, v1
	v_rcp_f32_e32 v1, v1
	ds_read_u16 v3, v135
	v_add_f32_e32 v2, 1.0, v2
	v_rcp_f32_e32 v2, v2
	v_mul_f32_e32 v1, v108, v1
	v_mul_f32_e32 v1, 0x3fb8aa3b, v1
	v_exp_f32_e32 v1, v1
	s_waitcnt lgkmcnt(0)
	v_lshlrev_b32_e32 v3, 16, v3
	v_mul_f32_e32 v2, v2, v3
	v_fma_f32 v36, -v1, v1, 1.0
	v_max_f32_e32 v36, 0, v36
	v_sqrt_f32_e32 v36, v36
	s_nop 0
	v_mul_f32_e32 v2, v2, v36
	ds_write_b32 v113, v1 offset:27840
	ds_write_b32 v113, v2 offset:44480
	v_add_f32_e32 v1, v103, v42
	v_mul_f32_e32 v1, 0xbfb8aa3b, v1
	v_exp_f32_e32 v1, v1
	v_add_f32_e32 v2, v104, v38
	v_mul_f32_e32 v2, 0xbfb8aa3b, v2
	v_exp_f32_e32 v2, v2
	v_add_f32_e32 v1, 1.0, v1
	v_rcp_f32_e32 v1, v1
	ds_read_u16 v3, v136
	v_add_f32_e32 v2, 1.0, v2
	v_rcp_f32_e32 v2, v2
	v_mul_f32_e32 v1, v108, v1
	v_mul_f32_e32 v1, 0x3fb8aa3b, v1
	v_exp_f32_e32 v1, v1
	s_waitcnt lgkmcnt(0)
	v_lshlrev_b32_e32 v3, 16, v3
	v_mul_f32_e32 v2, v2, v3
	v_fma_f32 v36, -v1, v1, 1.0
	v_max_f32_e32 v36, 0, v36
	v_sqrt_f32_e32 v36, v36
	s_nop 0
	v_mul_f32_e32 v2, v2, v36
	ds_write_b32 v111, v1 offset:27840
	ds_write_b32 v111, v2 offset:44480
	v_add_f32_e32 v1, v103, v43
	v_mul_f32_e32 v1, 0xbfb8aa3b, v1
	v_exp_f32_e32 v1, v1
	ds_read_u16 v3, v137
	v_add_f32_e32 v1, 1.0, v1
	v_rcp_f32_e32 v2, v1
	v_add_f32_e32 v1, v104, v39
	v_mul_f32_e32 v1, 0xbfb8aa3b, v1
	v_exp_f32_e32 v1, v1
	v_mul_f32_e32 v2, v108, v2
	v_mul_f32_e32 v2, 0x3fb8aa3b, v2
	v_exp_f32_e32 v2, v2
	v_add_f32_e32 v1, 1.0, v1
	v_rcp_f32_e32 v1, v1
	s_waitcnt lgkmcnt(0)
	v_lshlrev_b32_e32 v3, 16, v3
	v_fma_f32 v36, -v2, v2, 1.0
	v_max_f32_e32 v36, 0, v36
	v_sqrt_f32_e32 v36, v36
	v_mul_f32_e32 v1, v1, v3
	v_mul_f32_e32 v1, v36, v1
	ds_write_b32 v114, v2 offset:27840
	ds_write_b32 v114, v1 offset:44480
	s_waitcnt lgkmcnt(0)
	s_barrier
	s_and_saveexec_b64 s[4:5], s[10:11]
	s_cbranch_execz .LBB0_290
	s_and_b64 s[18:19], s[12:13], exec
	s_cselect_b32 s21, 0, 0x3ffc
	s_cselect_b32 s16, 1, -1
	s_mulk_i32 s16, 0x104
	v_and_b32_e32 v164, 0xff, v92
	v_lshl_add_u32 v164, v164, 2, s40
	v_add_u32_e32 v164, s21, v164
	s_lshl_b32 s17, s16, 3
	v_add_u32_e32 v165, s16, v164
	v_add_u32_e32 v166, s16, v165
	v_add_u32_e32 v167, s16, v166
	v_add_u32_e32 v168, s16, v167
	v_add_u32_e32 v169, s16, v168
	v_add_u32_e32 v170, s16, v169
	v_add_u32_e32 v171, s16, v170
	ds_read2st64_b32 v[148:149], v164 offset0:108 offset1:173
	ds_read2st64_b32 v[150:151], v165 offset0:108 offset1:173
	ds_read2st64_b32 v[152:153], v166 offset0:108 offset1:173
	ds_read2st64_b32 v[154:155], v167 offset0:108 offset1:173
	ds_read2st64_b32 v[156:157], v168 offset0:108 offset1:173
	ds_read2st64_b32 v[158:159], v169 offset0:108 offset1:173
	ds_read2st64_b32 v[160:161], v170 offset0:108 offset1:173
	ds_read2st64_b32 v[162:163], v171 offset0:108 offset1:173
	s_waitcnt lgkmcnt(7)
	v_fma_f32 v91, v91, v148, v149
	ds_write_b32 v164, v91 offset:44288
	v_add_u32_e32 v164, s17, v164
	ds_read2st64_b32 v[148:149], v164 offset0:108 offset1:173
	s_waitcnt lgkmcnt(8)
	v_fma_f32 v91, v91, v150, v151
	ds_write_b32 v165, v91 offset:44288
	v_add_u32_e32 v165, s17, v165
	ds_read2st64_b32 v[150:151], v165 offset0:108 offset1:173
	s_waitcnt lgkmcnt(9)
	v_fma_f32 v91, v91, v152, v153
	ds_write_b32 v166, v91 offset:44288
	v_add_u32_e32 v166, s17, v166
	ds_read2st64_b32 v[152:153], v166 offset0:108 offset1:173
	s_waitcnt lgkmcnt(10)
	v_fma_f32 v91, v91, v154, v155
	ds_write_b32 v167, v91 offset:44288
	v_add_u32_e32 v167, s17, v167
	ds_read2st64_b32 v[154:155], v167 offset0:108 offset1:173
	s_waitcnt lgkmcnt(11)
	v_fma_f32 v91, v91, v156, v157
	ds_write_b32 v168, v91 offset:44288
	v_add_u32_e32 v168, s17, v168
	ds_read2st64_b32 v[156:157], v168 offset0:108 offset1:173
	s_waitcnt lgkmcnt(12)
	v_fma_f32 v91, v91, v158, v159
	ds_write_b32 v169, v91 offset:44288
	v_add_u32_e32 v169, s17, v169
	ds_read2st64_b32 v[158:159], v169 offset0:108 offset1:173
	s_waitcnt lgkmcnt(13)
	v_fma_f32 v91, v91, v160, v161
	ds_write_b32 v170, v91 offset:44288
	v_add_u32_e32 v170, s17, v170
	ds_read2st64_b32 v[160:161], v170 offset0:108 offset1:173
	s_waitcnt lgkmcnt(14)
	v_fma_f32 v91, v91, v162, v163
	ds_write_b32 v171, v91 offset:44288
	v_add_u32_e32 v171, s17, v171
	ds_read2st64_b32 v[162:163], v171 offset0:108 offset1:173
	s_mov_b32 s15, 7
.Lscan_s:
	s_waitcnt lgkmcnt(14)
	v_fma_f32 v91, v91, v148, v149
	ds_write_b32 v164, v91 offset:44288
	v_add_u32_e32 v164, s17, v164
	ds_read2st64_b32 v[148:149], v164 offset0:108 offset1:173
	s_waitcnt lgkmcnt(14)
	v_fma_f32 v91, v91, v150, v151
	ds_write_b32 v165, v91 offset:44288
	v_add_u32_e32 v165, s17, v165
	ds_read2st64_b32 v[150:151], v165 offset0:108 offset1:173
	s_waitcnt lgkmcnt(14)
	v_fma_f32 v91, v91, v152, v153
	ds_write_b32 v166, v91 offset:44288
	v_add_u32_e32 v166, s17, v166
	ds_read2st64_b32 v[152:153], v166 offset0:108 offset1:173
	s_waitcnt lgkmcnt(14)
	v_fma_f32 v91, v91, v154, v155
	ds_write_b32 v167, v91 offset:44288
	v_add_u32_e32 v167, s17, v167
	ds_read2st64_b32 v[154:155], v167 offset0:108 offset1:173
	s_waitcnt lgkmcnt(14)
	v_fma_f32 v91, v91, v156, v157
	ds_write_b32 v168, v91 offset:44288
	v_add_u32_e32 v168, s17, v168
	ds_read2st64_b32 v[156:157], v168 offset0:108 offset1:173
	s_waitcnt lgkmcnt(14)
	v_fma_f32 v91, v91, v158, v159
	ds_write_b32 v169, v91 offset:44288
	v_add_u32_e32 v169, s17, v169
	ds_read2st64_b32 v[158:159], v169 offset0:108 offset1:173
	s_waitcnt lgkmcnt(14)
	v_fma_f32 v91, v91, v160, v161
	ds_write_b32 v170, v91 offset:44288
	v_add_u32_e32 v170, s17, v170
	ds_read2st64_b32 v[160:161], v170 offset0:108 offset1:173
	s_waitcnt lgkmcnt(14)
	v_fma_f32 v91, v91, v162, v163
	ds_write_b32 v171, v91 offset:44288
	v_add_u32_e32 v171, s17, v171
	ds_read2st64_b32 v[162:163], v171 offset0:108 offset1:173
	s_add_i32 s15, s15, -1
	s_cmp_lg_u32 s15, 0
	s_cbranch_scc1 .Lscan_s
	s_branch .LBB0_290
